# FFN-up SwiGLU epilogue rewritten by hand: same f32 ops per element, 8 independent chains per stage (no serial exp/rcp chain, no s_nop), direct use of hoisted rstd regs, constant row offsets; bit-ident
# baseline (speedup 1.0000x reference)
; __device__ __forceinline__ unsigned cvt_pk_bf16(float lo, float hi) { unsigned r; asm volatile("v_cvt_pk_bf16_f32 %0, %1, %2" : "=v"(r) : "v"(lo), "v"(hi)); return r; }
; __device__ __forceinline__ float silu_f(float x) { return x * __builtin_amdgcn_rcpf(1.0f + __builtin_amdgcn_exp2f(-1.4426950408889634f * x)); }
;     __device__ __forceinline__ void operator()(const f32x4 (&acc)[2][2][4][2], const Unit& u, int wr, int wc, int fr, int fq) const {
;     ...
;         for (int ai = 0; ai < 2; ++ai)
; #pragma unroll
;             for (int m = 0; m < 4; ++m) { bf16_t* rowp = O + (size_t)(row0 + ai * HALF + m * 16) * ldc + col0; const float r = rs[ai][m];
;                 const f32x4 g0 = acc[ai][0][m][0] * r, g1 = acc[ai][0][m][1] * r, u0 = acc[ai][1][m][0] * r, u1 = acc[ai][1][m][1] * r;
;                 f32x4 v0, v1;
; #pragma unroll
;                 for (int i = 0; i < 4; ++i) { v0[i] = silu_f(g0[i]) * u0[i]; v1[i] = silu_f(g1[i]) * u1[i]; }
;                 u32x4 w; w.x = cvt_pk_bf16(v0[0], v0[1]); w.y = cvt_pk_bf16(v0[2], v0[3]); w.z = cvt_pk_bf16(v1[0], v1[1]); w.w = cvt_pk_bf16(v1[2], v1[3]);
;                 *(u32x4*)rowp = w; }
.LBB0_1252:
	s_lshl_b32 s24, s22, 8
	s_ashr_i32 s25, s24, 31
	v_lshl_or_b32 v154, s23, 7, v159
	v_add_u32_e32 v161, s24, v1
	v_ashrrev_i32_e32 v155, 31, v154
	v_mov_b64_e32 v[152:153], s[10:11]
	s_movk_i32 s15, 0x1600
	v_mad_i64_i32 v[156:157], s[22:23], v161, s15, v[152:153]
	s_andn2_b64 vcc, exec, s[4:5]
	v_lshlrev_b64 v[162:163], 1, v[154:155]
	v_lshl_add_u64 v[156:157], v[156:157], 0, v[162:163]
	v_pk_mul_f32 v[134:135], v[134:135], v[242:243] op_sel_hi:[1,0]
	v_pk_mul_f32 v[136:137], v[136:137], v[242:243] op_sel_hi:[1,0]
	v_pk_mul_f32 v[126:127], v[126:127], v[242:243] op_sel_hi:[1,0]
	v_pk_mul_f32 v[128:129], v[128:129], v[242:243] op_sel_hi:[1,0]
	v_pk_mul_f32 v[130:131], v[130:131], v[242:243] op_sel_hi:[1,0]
	v_pk_mul_f32 v[132:133], v[132:133], v[242:243] op_sel_hi:[1,0]
	v_pk_mul_f32 v[122:123], v[122:123], v[242:243] op_sel_hi:[1,0]
	v_pk_mul_f32 v[124:125], v[124:125], v[242:243] op_sel_hi:[1,0]
	v_mul_f32_e32 v186, 0xbfb8aa3b, v134
	v_mul_f32_e32 v187, 0xbfb8aa3b, v135
	v_mul_f32_e32 v188, 0xbfb8aa3b, v136
	v_mul_f32_e32 v189, 0xbfb8aa3b, v137
	v_mul_f32_e32 v190, 0xbfb8aa3b, v126
	v_mul_f32_e32 v191, 0xbfb8aa3b, v127
	v_mul_f32_e32 v192, 0xbfb8aa3b, v128
	v_mul_f32_e32 v193, 0xbfb8aa3b, v129
	v_exp_f32_e32 v186, v186
	v_exp_f32_e32 v187, v187
	v_exp_f32_e32 v188, v188
	v_exp_f32_e32 v189, v189
	v_exp_f32_e32 v190, v190
	v_exp_f32_e32 v191, v191
	v_exp_f32_e32 v192, v192
	v_exp_f32_e32 v193, v193
	v_add_f32_e32 v186, 1.0, v186
	v_add_f32_e32 v187, 1.0, v187
	v_add_f32_e32 v188, 1.0, v188
	v_add_f32_e32 v189, 1.0, v189
	v_add_f32_e32 v190, 1.0, v190
	v_add_f32_e32 v191, 1.0, v191
	v_add_f32_e32 v192, 1.0, v192
	v_add_f32_e32 v193, 1.0, v193
	v_rcp_f32_e32 v186, v186
	v_rcp_f32_e32 v187, v187
	v_rcp_f32_e32 v188, v188
	v_rcp_f32_e32 v189, v189
	v_rcp_f32_e32 v190, v190
	v_rcp_f32_e32 v191, v191
	v_rcp_f32_e32 v192, v192
	v_rcp_f32_e32 v193, v193
	v_pk_mul_f32 v[134:135], v[134:135], v[186:187]
	v_pk_mul_f32 v[136:137], v[136:137], v[188:189]
	v_pk_mul_f32 v[126:127], v[126:127], v[190:191]
	v_pk_mul_f32 v[128:129], v[128:129], v[192:193]
	v_pk_mul_f32 v[130:131], v[130:131], v[134:135]
	v_pk_mul_f32 v[132:133], v[132:133], v[136:137]
	v_pk_mul_f32 v[122:123], v[122:123], v[126:127]
	v_pk_mul_f32 v[124:125], v[124:125], v[128:129]
	v_cvt_pk_bf16_f32 v202, v130, v131
	v_cvt_pk_bf16_f32 v203, v132, v133
	v_cvt_pk_bf16_f32 v204, v122, v123
	v_cvt_pk_bf16_f32 v205, v124, v125
	global_store_dwordx4 v[156:157], v[202:205], off
	v_pk_mul_f32 v[114:115], v[114:115], v[242:243] op_sel:[0,1]
	v_pk_mul_f32 v[116:117], v[116:117], v[242:243] op_sel:[0,1]
	v_pk_mul_f32 v[110:111], v[110:111], v[242:243] op_sel:[0,1]
	v_pk_mul_f32 v[112:113], v[112:113], v[242:243] op_sel:[0,1]
	v_pk_mul_f32 v[106:107], v[106:107], v[242:243] op_sel:[0,1]
	v_pk_mul_f32 v[108:109], v[108:109], v[242:243] op_sel:[0,1]
	v_pk_mul_f32 v[102:103], v[102:103], v[242:243] op_sel:[0,1]
	v_pk_mul_f32 v[104:105], v[104:105], v[242:243] op_sel:[0,1]
	v_mul_f32_e32 v194, 0xbfb8aa3b, v114
	v_mul_f32_e32 v195, 0xbfb8aa3b, v115
	v_mul_f32_e32 v196, 0xbfb8aa3b, v116
	v_mul_f32_e32 v197, 0xbfb8aa3b, v117
	v_mul_f32_e32 v198, 0xbfb8aa3b, v110
	v_mul_f32_e32 v199, 0xbfb8aa3b, v111
	v_mul_f32_e32 v200, 0xbfb8aa3b, v112
	v_mul_f32_e32 v201, 0xbfb8aa3b, v113
	v_exp_f32_e32 v194, v194
	v_exp_f32_e32 v195, v195
	v_exp_f32_e32 v196, v196
	v_exp_f32_e32 v197, v197
	v_exp_f32_e32 v198, v198
	v_exp_f32_e32 v199, v199
	v_exp_f32_e32 v200, v200
	v_exp_f32_e32 v201, v201
	v_add_f32_e32 v194, 1.0, v194
	v_add_f32_e32 v195, 1.0, v195
	v_add_f32_e32 v196, 1.0, v196
	v_add_f32_e32 v197, 1.0, v197
	v_add_f32_e32 v198, 1.0, v198
	v_add_f32_e32 v199, 1.0, v199
	v_add_f32_e32 v200, 1.0, v200
	v_add_f32_e32 v201, 1.0, v201
	v_rcp_f32_e32 v194, v194
	v_rcp_f32_e32 v195, v195
	v_rcp_f32_e32 v196, v196
	v_rcp_f32_e32 v197, v197
	v_rcp_f32_e32 v198, v198
	v_rcp_f32_e32 v199, v199
	v_rcp_f32_e32 v200, v200
	v_rcp_f32_e32 v201, v201
	v_pk_mul_f32 v[114:115], v[114:115], v[194:195]
	v_pk_mul_f32 v[116:117], v[116:117], v[196:197]
	v_pk_mul_f32 v[110:111], v[110:111], v[198:199]
	v_pk_mul_f32 v[112:113], v[112:113], v[200:201]
	v_pk_mul_f32 v[106:107], v[106:107], v[114:115]
	v_pk_mul_f32 v[108:109], v[108:109], v[116:117]
	v_pk_mul_f32 v[102:103], v[102:103], v[110:111]
	v_pk_mul_f32 v[104:105], v[104:105], v[112:113]
	v_cvt_pk_bf16_f32 v206, v106, v107
	v_cvt_pk_bf16_f32 v207, v108, v109
	v_cvt_pk_bf16_f32 v208, v102, v103
	v_cvt_pk_bf16_f32 v209, v104, v105
	s_mov_b32 s24, 0x16000
	v_lshl_add_u64 v[212:213], s[24:25], 0, v[156:157]
	global_store_dwordx4 v[212:213], v[206:209], off
	v_pk_mul_f32 v[98:99], v[98:99], v[244:245] op_sel_hi:[1,0]
	v_pk_mul_f32 v[100:101], v[100:101], v[244:245] op_sel_hi:[1,0]
	v_pk_mul_f32 v[94:95], v[94:95], v[244:245] op_sel_hi:[1,0]
	v_pk_mul_f32 v[96:97], v[96:97], v[244:245] op_sel_hi:[1,0]
	v_pk_mul_f32 v[90:91], v[90:91], v[244:245] op_sel_hi:[1,0]
	v_pk_mul_f32 v[92:93], v[92:93], v[244:245] op_sel_hi:[1,0]
	v_pk_mul_f32 v[86:87], v[86:87], v[244:245] op_sel_hi:[1,0]
	v_pk_mul_f32 v[88:89], v[88:89], v[244:245] op_sel_hi:[1,0]
	v_mul_f32_e32 v186, 0xbfb8aa3b, v98
	v_mul_f32_e32 v187, 0xbfb8aa3b, v99
	v_mul_f32_e32 v188, 0xbfb8aa3b, v100
	v_mul_f32_e32 v189, 0xbfb8aa3b, v101
	v_mul_f32_e32 v190, 0xbfb8aa3b, v94
	v_mul_f32_e32 v191, 0xbfb8aa3b, v95
	v_mul_f32_e32 v192, 0xbfb8aa3b, v96
	v_mul_f32_e32 v193, 0xbfb8aa3b, v97
	v_exp_f32_e32 v186, v186
	v_exp_f32_e32 v187, v187
	v_exp_f32_e32 v188, v188
	v_exp_f32_e32 v189, v189
	v_exp_f32_e32 v190, v190
	v_exp_f32_e32 v191, v191
	v_exp_f32_e32 v192, v192
	v_exp_f32_e32 v193, v193
	v_add_f32_e32 v186, 1.0, v186
; __device__ __forceinline__ unsigned cvt_pk_bf16(float lo, float hi) { unsigned r; asm volatile("v_cvt_pk_bf16_f32 %0, %1, %2" : "=v"(r) : "v"(lo), "v"(hi)); return r; }
; __device__ __forceinline__ float silu_f(float x) { return x * __builtin_amdgcn_rcpf(1.0f + __builtin_amdgcn_exp2f(-1.4426950408889634f * x)); }
;     __device__ __forceinline__ void operator()(const f32x4 (&acc)[2][2][4][2], const Unit& u, int wr, int wc, int fr, int fq) const {
;     ...
;         for (int ai = 0; ai < 2; ++ai)
; #pragma unroll
;             for (int m = 0; m < 4; ++m) { bf16_t* rowp = O + (size_t)(row0 + ai * HALF + m * 16) * ldc + col0; const float r = rs[ai][m];
;                 const f32x4 g0 = acc[ai][0][m][0] * r, g1 = acc[ai][0][m][1] * r, u0 = acc[ai][1][m][0] * r, u1 = acc[ai][1][m][1] * r;
;                 f32x4 v0, v1;
; #pragma unroll
;                 for (int i = 0; i < 4; ++i) { v0[i] = silu_f(g0[i]) * u0[i]; v1[i] = silu_f(g1[i]) * u1[i]; }
;                 u32x4 w; w.x = cvt_pk_bf16(v0[0], v0[1]); w.y = cvt_pk_bf16(v0[2], v0[3]); w.z = cvt_pk_bf16(v1[0], v1[1]); w.w = cvt_pk_bf16(v1[2], v1[3]);
;                 *(u32x4*)rowp = w; }
	v_add_f32_e32 v187, 1.0, v187
	v_add_f32_e32 v188, 1.0, v188
	v_add_f32_e32 v189, 1.0, v189
	v_add_f32_e32 v190, 1.0, v190
	v_add_f32_e32 v191, 1.0, v191
	v_add_f32_e32 v192, 1.0, v192
	v_add_f32_e32 v193, 1.0, v193
	v_rcp_f32_e32 v186, v186
	v_rcp_f32_e32 v187, v187
	v_rcp_f32_e32 v188, v188
	v_rcp_f32_e32 v189, v189
	v_rcp_f32_e32 v190, v190
	v_rcp_f32_e32 v191, v191
	v_rcp_f32_e32 v192, v192
	v_rcp_f32_e32 v193, v193
	v_pk_mul_f32 v[98:99], v[98:99], v[186:187]
	v_pk_mul_f32 v[100:101], v[100:101], v[188:189]
	v_pk_mul_f32 v[94:95], v[94:95], v[190:191]
	v_pk_mul_f32 v[96:97], v[96:97], v[192:193]
	v_pk_mul_f32 v[90:91], v[90:91], v[98:99]
	v_pk_mul_f32 v[92:93], v[92:93], v[100:101]
	v_pk_mul_f32 v[86:87], v[86:87], v[94:95]
	v_pk_mul_f32 v[88:89], v[88:89], v[96:97]
	v_cvt_pk_bf16_f32 v202, v90, v91
	v_cvt_pk_bf16_f32 v203, v92, v93
	v_cvt_pk_bf16_f32 v204, v86, v87
	v_cvt_pk_bf16_f32 v205, v88, v89
	s_mov_b32 s24, 0x2c000
	v_lshl_add_u64 v[210:211], s[24:25], 0, v[156:157]
	global_store_dwordx4 v[210:211], v[202:205], off
	v_pk_mul_f32 v[82:83], v[82:83], v[244:245] op_sel:[0,1]
	v_pk_mul_f32 v[84:85], v[84:85], v[244:245] op_sel:[0,1]
	v_pk_mul_f32 v[78:79], v[78:79], v[244:245] op_sel:[0,1]
	v_pk_mul_f32 v[80:81], v[80:81], v[244:245] op_sel:[0,1]
	v_pk_mul_f32 v[74:75], v[74:75], v[244:245] op_sel:[0,1]
	v_pk_mul_f32 v[76:77], v[76:77], v[244:245] op_sel:[0,1]
	v_pk_mul_f32 v[70:71], v[70:71], v[244:245] op_sel:[0,1]
	v_pk_mul_f32 v[72:73], v[72:73], v[244:245] op_sel:[0,1]
	v_mul_f32_e32 v194, 0xbfb8aa3b, v82
	v_mul_f32_e32 v195, 0xbfb8aa3b, v83
	v_mul_f32_e32 v196, 0xbfb8aa3b, v84
	v_mul_f32_e32 v197, 0xbfb8aa3b, v85
	v_mul_f32_e32 v198, 0xbfb8aa3b, v78
	v_mul_f32_e32 v199, 0xbfb8aa3b, v79
	v_mul_f32_e32 v200, 0xbfb8aa3b, v80
	v_mul_f32_e32 v201, 0xbfb8aa3b, v81
	v_exp_f32_e32 v194, v194
	v_exp_f32_e32 v195, v195
	v_exp_f32_e32 v196, v196
	v_exp_f32_e32 v197, v197
	v_exp_f32_e32 v198, v198
	v_exp_f32_e32 v199, v199
	v_exp_f32_e32 v200, v200
	v_exp_f32_e32 v201, v201
	v_add_f32_e32 v194, 1.0, v194
	v_add_f32_e32 v195, 1.0, v195
	v_add_f32_e32 v196, 1.0, v196
	v_add_f32_e32 v197, 1.0, v197
	v_add_f32_e32 v198, 1.0, v198
	v_add_f32_e32 v199, 1.0, v199
	v_add_f32_e32 v200, 1.0, v200
	v_add_f32_e32 v201, 1.0, v201
	v_rcp_f32_e32 v194, v194
	v_rcp_f32_e32 v195, v195
	v_rcp_f32_e32 v196, v196
	v_rcp_f32_e32 v197, v197
	v_rcp_f32_e32 v198, v198
	v_rcp_f32_e32 v199, v199
	v_rcp_f32_e32 v200, v200
	v_rcp_f32_e32 v201, v201
	v_pk_mul_f32 v[82:83], v[82:83], v[194:195]
	v_pk_mul_f32 v[84:85], v[84:85], v[196:197]
	v_pk_mul_f32 v[78:79], v[78:79], v[198:199]
	v_pk_mul_f32 v[80:81], v[80:81], v[200:201]
	v_pk_mul_f32 v[74:75], v[74:75], v[82:83]
	v_pk_mul_f32 v[76:77], v[76:77], v[84:85]
	v_pk_mul_f32 v[70:71], v[70:71], v[78:79]
	v_pk_mul_f32 v[72:73], v[72:73], v[80:81]
	v_cvt_pk_bf16_f32 v206, v74, v75
	v_cvt_pk_bf16_f32 v207, v76, v77
	v_cvt_pk_bf16_f32 v208, v70, v71
	v_cvt_pk_bf16_f32 v209, v72, v73
	s_mov_b32 s24, 0x42000
	v_lshl_add_u64 v[212:213], s[24:25], 0, v[156:157]
	global_store_dwordx4 v[212:213], v[206:209], off
	v_pk_mul_f32 v[62:63], v[62:63], v[246:247] op_sel_hi:[1,0]
	v_pk_mul_f32 v[64:65], v[64:65], v[246:247] op_sel_hi:[1,0]
	v_pk_mul_f32 v[58:59], v[58:59], v[246:247] op_sel_hi:[1,0]
	v_pk_mul_f32 v[60:61], v[60:61], v[246:247] op_sel_hi:[1,0]
	v_pk_mul_f32 v[54:55], v[54:55], v[246:247] op_sel_hi:[1,0]
	v_pk_mul_f32 v[56:57], v[56:57], v[246:247] op_sel_hi:[1,0]
	v_pk_mul_f32 v[50:51], v[50:51], v[246:247] op_sel_hi:[1,0]
	v_pk_mul_f32 v[52:53], v[52:53], v[246:247] op_sel_hi:[1,0]
	v_mul_f32_e32 v186, 0xbfb8aa3b, v62
	v_mul_f32_e32 v187, 0xbfb8aa3b, v63
	v_mul_f32_e32 v188, 0xbfb8aa3b, v64
	v_mul_f32_e32 v189, 0xbfb8aa3b, v65
	v_mul_f32_e32 v190, 0xbfb8aa3b, v58
	v_mul_f32_e32 v191, 0xbfb8aa3b, v59
	v_mul_f32_e32 v192, 0xbfb8aa3b, v60
	v_mul_f32_e32 v193, 0xbfb8aa3b, v61
	v_exp_f32_e32 v186, v186
	v_exp_f32_e32 v187, v187
	v_exp_f32_e32 v188, v188
	v_exp_f32_e32 v189, v189
	v_exp_f32_e32 v190, v190
	v_exp_f32_e32 v191, v191
	v_exp_f32_e32 v192, v192
	v_exp_f32_e32 v193, v193
	v_add_f32_e32 v186, 1.0, v186
	v_add_f32_e32 v187, 1.0, v187
	v_add_f32_e32 v188, 1.0, v188
	v_add_f32_e32 v189, 1.0, v189
	v_add_f32_e32 v190, 1.0, v190
	v_add_f32_e32 v191, 1.0, v191
	v_add_f32_e32 v192, 1.0, v192
	v_add_f32_e32 v193, 1.0, v193
	v_rcp_f32_e32 v186, v186
	v_rcp_f32_e32 v187, v187
	v_rcp_f32_e32 v188, v188
	v_rcp_f32_e32 v189, v189
	v_rcp_f32_e32 v190, v190
	v_rcp_f32_e32 v191, v191
	v_rcp_f32_e32 v192, v192
	v_rcp_f32_e32 v193, v193
	v_pk_mul_f32 v[62:63], v[62:63], v[186:187]
	v_pk_mul_f32 v[64:65], v[64:65], v[188:189]
	v_pk_mul_f32 v[58:59], v[58:59], v[190:191]
	v_pk_mul_f32 v[60:61], v[60:61], v[192:193]
	v_pk_mul_f32 v[54:55], v[54:55], v[62:63]
	v_pk_mul_f32 v[56:57], v[56:57], v[64:65]
	v_pk_mul_f32 v[50:51], v[50:51], v[58:59]
	v_pk_mul_f32 v[52:53], v[52:53], v[60:61]
	v_cvt_pk_bf16_f32 v202, v54, v55
	v_cvt_pk_bf16_f32 v203, v56, v57
	v_cvt_pk_bf16_f32 v204, v50, v51
	v_cvt_pk_bf16_f32 v205, v52, v53
	s_mov_b32 s24, 0xb0000
	v_lshl_add_u64 v[210:211], s[24:25], 0, v[156:157]
	global_store_dwordx4 v[210:211], v[202:205], off
	v_pk_mul_f32 v[46:47], v[46:47], v[246:247] op_sel:[0,1]
	v_pk_mul_f32 v[48:49], v[48:49], v[246:247] op_sel:[0,1]
	v_pk_mul_f32 v[42:43], v[42:43], v[246:247] op_sel:[0,1]
	v_pk_mul_f32 v[44:45], v[44:45], v[246:247] op_sel:[0,1]
	v_pk_mul_f32 v[38:39], v[38:39], v[246:247] op_sel:[0,1]
	v_pk_mul_f32 v[40:41], v[40:41], v[246:247] op_sel:[0,1]
	v_pk_mul_f32 v[34:35], v[34:35], v[246:247] op_sel:[0,1]
	v_pk_mul_f32 v[36:37], v[36:37], v[246:247] op_sel:[0,1]
	v_mul_f32_e32 v194, 0xbfb8aa3b, v46
; __device__ __forceinline__ unsigned cvt_pk_bf16(float lo, float hi) { unsigned r; asm volatile("v_cvt_pk_bf16_f32 %0, %1, %2" : "=v"(r) : "v"(lo), "v"(hi)); return r; }
; __device__ __forceinline__ float silu_f(float x) { return x * __builtin_amdgcn_rcpf(1.0f + __builtin_amdgcn_exp2f(-1.4426950408889634f * x)); }
;     __device__ __forceinline__ void operator()(const f32x4 (&acc)[2][2][4][2], const Unit& u, int wr, int wc, int fr, int fq) const {
;     ...
;         for (int ai = 0; ai < 2; ++ai)
; #pragma unroll
;             for (int m = 0; m < 4; ++m) { bf16_t* rowp = O + (size_t)(row0 + ai * HALF + m * 16) * ldc + col0; const float r = rs[ai][m];
;                 const f32x4 g0 = acc[ai][0][m][0] * r, g1 = acc[ai][0][m][1] * r, u0 = acc[ai][1][m][0] * r, u1 = acc[ai][1][m][1] * r;
;                 f32x4 v0, v1;
; #pragma unroll
;                 for (int i = 0; i < 4; ++i) { v0[i] = silu_f(g0[i]) * u0[i]; v1[i] = silu_f(g1[i]) * u1[i]; }
;                 u32x4 w; w.x = cvt_pk_bf16(v0[0], v0[1]); w.y = cvt_pk_bf16(v0[2], v0[3]); w.z = cvt_pk_bf16(v1[0], v1[1]); w.w = cvt_pk_bf16(v1[2], v1[3]);
;                 *(u32x4*)rowp = w; }
	v_mul_f32_e32 v195, 0xbfb8aa3b, v47
	v_mul_f32_e32 v196, 0xbfb8aa3b, v48
	v_mul_f32_e32 v197, 0xbfb8aa3b, v49
	v_mul_f32_e32 v198, 0xbfb8aa3b, v42
	v_mul_f32_e32 v199, 0xbfb8aa3b, v43
	v_mul_f32_e32 v200, 0xbfb8aa3b, v44
	v_mul_f32_e32 v201, 0xbfb8aa3b, v45
	v_exp_f32_e32 v194, v194
	v_exp_f32_e32 v195, v195
	v_exp_f32_e32 v196, v196
	v_exp_f32_e32 v197, v197
	v_exp_f32_e32 v198, v198
	v_exp_f32_e32 v199, v199
	v_exp_f32_e32 v200, v200
	v_exp_f32_e32 v201, v201
	v_add_f32_e32 v194, 1.0, v194
	v_add_f32_e32 v195, 1.0, v195
	v_add_f32_e32 v196, 1.0, v196
	v_add_f32_e32 v197, 1.0, v197
	v_add_f32_e32 v198, 1.0, v198
	v_add_f32_e32 v199, 1.0, v199
	v_add_f32_e32 v200, 1.0, v200
	v_add_f32_e32 v201, 1.0, v201
	v_rcp_f32_e32 v194, v194
	v_rcp_f32_e32 v195, v195
	v_rcp_f32_e32 v196, v196
	v_rcp_f32_e32 v197, v197
	v_rcp_f32_e32 v198, v198
	v_rcp_f32_e32 v199, v199
	v_rcp_f32_e32 v200, v200
	v_rcp_f32_e32 v201, v201
	v_pk_mul_f32 v[46:47], v[46:47], v[194:195]
	v_pk_mul_f32 v[48:49], v[48:49], v[196:197]
	v_pk_mul_f32 v[42:43], v[42:43], v[198:199]
	v_pk_mul_f32 v[44:45], v[44:45], v[200:201]
	v_pk_mul_f32 v[38:39], v[38:39], v[46:47]
	v_pk_mul_f32 v[40:41], v[40:41], v[48:49]
	v_pk_mul_f32 v[34:35], v[34:35], v[42:43]
	v_pk_mul_f32 v[36:37], v[36:37], v[44:45]
	v_cvt_pk_bf16_f32 v206, v38, v39
	v_cvt_pk_bf16_f32 v207, v40, v41
	v_cvt_pk_bf16_f32 v208, v34, v35
	v_cvt_pk_bf16_f32 v209, v36, v37
	s_mov_b32 s24, 0xc6000
	v_lshl_add_u64 v[212:213], s[24:25], 0, v[156:157]
	global_store_dwordx4 v[212:213], v[206:209], off
	v_pk_mul_f32 v[30:31], v[30:31], v[248:249] op_sel_hi:[1,0]
	v_pk_mul_f32 v[32:33], v[32:33], v[248:249] op_sel_hi:[1,0]
	v_pk_mul_f32 v[26:27], v[26:27], v[248:249] op_sel_hi:[1,0]
	v_pk_mul_f32 v[28:29], v[28:29], v[248:249] op_sel_hi:[1,0]
	v_pk_mul_f32 v[22:23], v[22:23], v[248:249] op_sel_hi:[1,0]
	v_pk_mul_f32 v[24:25], v[24:25], v[248:249] op_sel_hi:[1,0]
	v_pk_mul_f32 v[18:19], v[18:19], v[248:249] op_sel_hi:[1,0]
	v_pk_mul_f32 v[20:21], v[20:21], v[248:249] op_sel_hi:[1,0]
	v_mul_f32_e32 v186, 0xbfb8aa3b, v30
	v_mul_f32_e32 v187, 0xbfb8aa3b, v31
	v_mul_f32_e32 v188, 0xbfb8aa3b, v32
	v_mul_f32_e32 v189, 0xbfb8aa3b, v33
	v_mul_f32_e32 v190, 0xbfb8aa3b, v26
	v_mul_f32_e32 v191, 0xbfb8aa3b, v27
	v_mul_f32_e32 v192, 0xbfb8aa3b, v28
	v_mul_f32_e32 v193, 0xbfb8aa3b, v29
	v_exp_f32_e32 v186, v186
	v_exp_f32_e32 v187, v187
	v_exp_f32_e32 v188, v188
	v_exp_f32_e32 v189, v189
	v_exp_f32_e32 v190, v190
	v_exp_f32_e32 v191, v191
	v_exp_f32_e32 v192, v192
	v_exp_f32_e32 v193, v193
	v_add_f32_e32 v186, 1.0, v186
	v_add_f32_e32 v187, 1.0, v187
	v_add_f32_e32 v188, 1.0, v188
	v_add_f32_e32 v189, 1.0, v189
	v_add_f32_e32 v190, 1.0, v190
	v_add_f32_e32 v191, 1.0, v191
	v_add_f32_e32 v192, 1.0, v192
	v_add_f32_e32 v193, 1.0, v193
	v_rcp_f32_e32 v186, v186
	v_rcp_f32_e32 v187, v187
	v_rcp_f32_e32 v188, v188
	v_rcp_f32_e32 v189, v189
	v_rcp_f32_e32 v190, v190
	v_rcp_f32_e32 v191, v191
	v_rcp_f32_e32 v192, v192
	v_rcp_f32_e32 v193, v193
	v_pk_mul_f32 v[30:31], v[30:31], v[186:187]
	v_pk_mul_f32 v[32:33], v[32:33], v[188:189]
	v_pk_mul_f32 v[26:27], v[26:27], v[190:191]
	v_pk_mul_f32 v[28:29], v[28:29], v[192:193]
	v_pk_mul_f32 v[22:23], v[22:23], v[30:31]
	v_pk_mul_f32 v[24:25], v[24:25], v[32:33]
	v_pk_mul_f32 v[18:19], v[18:19], v[26:27]
	v_pk_mul_f32 v[20:21], v[20:21], v[28:29]
	v_cvt_pk_bf16_f32 v202, v22, v23
	v_cvt_pk_bf16_f32 v203, v24, v25
	v_cvt_pk_bf16_f32 v204, v18, v19
	v_cvt_pk_bf16_f32 v205, v20, v21
	s_mov_b32 s24, 0xdc000
	v_lshl_add_u64 v[210:211], s[24:25], 0, v[156:157]
	global_store_dwordx4 v[210:211], v[202:205], off
	v_pk_mul_f32 v[14:15], v[14:15], v[248:249] op_sel:[0,1]
	v_pk_mul_f32 v[16:17], v[16:17], v[248:249] op_sel:[0,1]
	v_pk_mul_f32 v[10:11], v[10:11], v[248:249] op_sel:[0,1]
	v_pk_mul_f32 v[12:13], v[12:13], v[248:249] op_sel:[0,1]
	v_pk_mul_f32 v[6:7], v[6:7], v[248:249] op_sel:[0,1]
	v_pk_mul_f32 v[8:9], v[8:9], v[248:249] op_sel:[0,1]
	v_pk_mul_f32 v[2:3], v[2:3], v[248:249] op_sel:[0,1]
	v_pk_mul_f32 v[4:5], v[4:5], v[248:249] op_sel:[0,1]
	v_mul_f32_e32 v194, 0xbfb8aa3b, v14
	v_mul_f32_e32 v195, 0xbfb8aa3b, v15
	v_mul_f32_e32 v196, 0xbfb8aa3b, v16
	v_mul_f32_e32 v197, 0xbfb8aa3b, v17
	v_mul_f32_e32 v198, 0xbfb8aa3b, v10
	v_mul_f32_e32 v199, 0xbfb8aa3b, v11
	v_mul_f32_e32 v200, 0xbfb8aa3b, v12
	v_mul_f32_e32 v201, 0xbfb8aa3b, v13
	v_exp_f32_e32 v194, v194
	v_exp_f32_e32 v195, v195
	v_exp_f32_e32 v196, v196
	v_exp_f32_e32 v197, v197
	v_exp_f32_e32 v198, v198
	v_exp_f32_e32 v199, v199
	v_exp_f32_e32 v200, v200
	v_exp_f32_e32 v201, v201
	v_add_f32_e32 v194, 1.0, v194
	v_add_f32_e32 v195, 1.0, v195
	v_add_f32_e32 v196, 1.0, v196
	v_add_f32_e32 v197, 1.0, v197
	v_add_f32_e32 v198, 1.0, v198
	v_add_f32_e32 v199, 1.0, v199
	v_add_f32_e32 v200, 1.0, v200
	v_add_f32_e32 v201, 1.0, v201
	v_rcp_f32_e32 v194, v194
	v_rcp_f32_e32 v195, v195
	v_rcp_f32_e32 v196, v196
	v_rcp_f32_e32 v197, v197
	v_rcp_f32_e32 v198, v198
	v_rcp_f32_e32 v199, v199
	v_rcp_f32_e32 v200, v200
	v_rcp_f32_e32 v201, v201
	v_pk_mul_f32 v[14:15], v[14:15], v[194:195]
	v_pk_mul_f32 v[16:17], v[16:17], v[196:197]
	v_pk_mul_f32 v[10:11], v[10:11], v[198:199]
	v_pk_mul_f32 v[12:13], v[12:13], v[200:201]
	v_pk_mul_f32 v[6:7], v[6:7], v[14:15]
	v_pk_mul_f32 v[8:9], v[8:9], v[16:17]
	v_pk_mul_f32 v[2:3], v[2:3], v[10:11]
	v_pk_mul_f32 v[4:5], v[4:5], v[12:13]
	v_cvt_pk_bf16_f32 v206, v6, v7
	v_cvt_pk_bf16_f32 v207, v8, v9
	v_cvt_pk_bf16_f32 v208, v2, v3
	v_cvt_pk_bf16_f32 v209, v4, v5
	s_mov_b32 s24, 0xf2000
	v_lshl_add_u64 v[212:213], s[24:25], 0, v[156:157]
	global_store_dwordx4 v[212:213], v[206:209], off
	s_mov_b64 s[22:23], -1
	s_cbranch_vccnz .LBB0_1245
	s_andn2_b64 vcc, exec, s[6:7]
	s_cbranch_vccnz .LBB0_1244
	s_barrier
	s_branch .LBB0_1244
